# P5 epilogue loads hoisted with counted vmcnt + batched cross-lane reduce; attention pass 1 hand software-pipelined
# speedup vs baseline: 1.0529x; 1.0529x over previous
.LBB0_209:
	s_bfe_u32 s14, s77, 0x30005
	s_lshl_b32 s15, s14, 22
	s_add_u32 s18, s31, s15
	s_addc_u32 s19, s34, 0
	s_and_b32 s12, s77, 7
	s_xor_b32 s22, s12, 15
	s_cmpk_lt_u32 s77, 0x100
	v_mov_b32_e32 v74, v165
	s_cselect_b32 s22, s12, s22
	s_bfe_u32 s24, s77, 0x20003
	v_readfirstlane_b32 s12, v74
	s_ashr_i32 s25, s12, 6
	s_lshl_b32 s29, s25, 3
	s_lshl_b32 s23, s25, 1
	s_or_b32 s53, s29, 4
	s_lshl_b32 s27, s14, 12
	s_lshl_b32 s26, s22, 2
	s_ashr_i32 s39, s12, 7
	s_lshl_b32 s12, s24, 8
	s_and_b32 s38, s23, 2
	s_bfe_u32 s54, s53, 0x20002
	s_lshl_b32 s55, s22, 8
	s_lshl_b32 s28, s14, 21
	s_add_u32 s22, s78, s15
	s_addc_u32 s23, s79, 0
	s_lshl_b32 s15, s25, 5
	s_or_b32 s14, s55, s27
	s_ashr_i32 s27, s15, 31
	s_add_u32 s14, s15, s14
	v_and_b32_e32 v168, 31, v74
	s_addc_u32 s15, s27, 0
	v_or_b32_e32 v0, s14, v168
	v_mov_b32_e32 v1, s15
	v_lshlrev_b64 v[0:1], 10, v[0:1]
	v_bfe_u32 v183, v74, 5, 1
	v_lshl_add_u64 v[0:1], s[46:47], 0, v[0:1]
	v_lshl_add_u64 v[0:1], v[0:1], 0, s[12:13]
	v_lshlrev_b32_e32 v166, 4, v183
	v_lshl_add_u64 v[0:1], v[0:1], 0, v[166:167]
	global_load_dwordx4 v[128:131], v[0:1], off offset:224
	global_load_dwordx4 v[132:135], v[0:1], off offset:192
	global_load_dwordx4 v[144:147], v[0:1], off offset:96
	global_load_dwordx4 v[148:151], v[0:1], off offset:64
	global_load_dwordx4 v[136:139], v[0:1], off offset:160
	global_load_dwordx4 v[140:143], v[0:1], off offset:128
	global_load_dwordx4 v[152:155], v[0:1], off offset:32
	global_load_dwordx4 v[156:159], v[0:1], off
	v_lshlrev_b32_e32 v2, 2, v74
	v_bfe_u32 v0, v74, 4, 2
	v_bfe_u32 v75, v74, 2, 2
	v_and_b32_e32 v2, 12, v2
	v_or_b32_e32 v5, 8, v183
	v_or_b32_e32 v76, 2, v183
	v_or_b32_e32 v6, 10, v183
	v_or_b32_e32 v7, 4, v183
	v_or_b32_e32 v8, 12, v183
	v_or_b32_e32 v9, 6, v183
	v_or_b32_e32 v10, 14, v183
	v_and_b32_e32 v1, 15, v74
	v_lshlrev_b32_e32 v3, 2, v0
	v_lshlrev_b32_e32 v4, 8, v168
	v_bitop3_b32 v11, v2, v183, v75 bitop3:0x36
	v_bitop3_b32 v5, v2, v5, v75 bitop3:0x36
	v_bitop3_b32 v12, v2, v76, v75 bitop3:0x36
	v_bitop3_b32 v6, v2, v6, v75 bitop3:0x36
	v_bitop3_b32 v7, v2, v7, v75 bitop3:0x36
	v_bitop3_b32 v8, v2, v8, v75 bitop3:0x36
	v_bitop3_b32 v9, v2, v9, v75 bitop3:0x36
	v_bitop3_b32 v2, v2, v10, v75 bitop3:0x36
	v_lshl_or_b32 v191, v11, 4, v4
	v_lshl_or_b32 v187, v5, 4, v4
	v_lshl_or_b32 v190, v12, 4, v4
	v_lshl_or_b32 v186, v6, 4, v4
	v_lshl_or_b32 v189, v7, 4, v4
	v_lshl_or_b32 v185, v8, 4, v4
	v_lshl_or_b32 v188, v9, 4, v4
	v_lshl_or_b32 v184, v2, 4, v4
	v_or_b32_e32 v2, s29, v0
	v_bitop3_b32 v4, s38, v1, v3 bitop3:0x36
	v_lshlrev_b32_e32 v2, 10, v2
	v_or_b32_e32 v0, s53, v0
	v_lshlrev_b32_e32 v4, 4, v4
	v_bitop3_b32 v1, s54, v1, v3 bitop3:0x36
	s_lshl_b32 s56, s25, 11
	v_lshlrev_b32_e32 v0, 10, v0
	v_or3_b32 v166, v4, v2, s12
	v_lshlrev_b32_e32 v1, 4, v1
	s_or_b32 s55, s56, 0x400
	v_mov_b32_e32 v171, v167
	v_or3_b32 v170, v1, v0, s12
	s_lshl_b32 s12, s24, 7
	s_add_i32 s39, s39, s26
	s_add_i32 s38, s56, 0
	s_add_i32 s57, s55, 0
	v_lshl_add_u64 v[70:71], s[22:23], 0, v[166:167]
	v_lshl_add_u64 v[64:65], s[22:23], 0, v[170:171]
	s_add_u32 s24, s22, 0x10000
	s_mov_b32 s27, 2
	v_mov_b32_e32 v72, v167
	v_mov_b32_e32 v73, v167
	s_mov_b32 s54, 0
	s_addc_u32 s25, s23, 0
	s_waitcnt vmcnt(0)
	s_mov_b32 vcc_hi, m0
	s_mov_b32 m0, s38
	s_nop 0
	global_load_lds_dwordx4 v[70:71], off
	s_mov_b32 m0, s57
	s_nop 0
	global_load_lds_dwordx4 v[64:65], off
	v_lshl_add_u64 v[66:67], s[24:25], 0, v[166:167]
	s_add_i32 s58, s56, s36
	s_mov_b32 m0, s58
	s_nop 0
	global_load_lds_dwordx4 v[66:67], off
	v_lshl_add_u64 v[68:69], s[24:25], 0, v[170:171]
	s_add_i32 s59, s55, s36
	s_mov_b32 m0, s59
	s_nop 0
	global_load_lds_dwordx4 v[68:69], off
	s_or_b32 s53, s26, 2
	s_add_i32 s29, s26, 4
	s_mov_b64 s[24:25], s[18:19]
	s_add_i32 vcc_lo, s39, 1
	s_mov_b32 s60, 0
	s_mov_b32 s61, 0x8000
	v_mov_b32_e32 v32, 0xff800000
	v_mov_b32_e32 v33, v32
	v_mov_b32_e32 v34, v32
	v_mov_b32_e32 v35, v32
	v_mov_b32_e32 v36, v32
	v_mov_b32_e32 v37, v32
	v_mov_b32_e32 v38, v32
	v_mov_b32_e32 v39, v32
	v_mov_b32_e32 v40, v32
	v_mov_b32_e32 v41, v32
	v_mov_b32_e32 v42, v32
	v_mov_b32_e32 v43, v32
	v_mov_b32_e32 v44, v32
	v_mov_b32_e32 v45, v32
	v_mov_b32_e32 v46, v32
	v_mov_b32_e32 v47, v32
	v_mov_b32_e32 v48, v32
	v_mov_b32_e32 v49, v32
	v_mov_b32_e32 v50, v32
	v_mov_b32_e32 v51, v32
	v_mov_b32_e32 v52, v32
	v_mov_b32_e32 v53, v32
	v_mov_b32_e32 v54, v32
	v_mov_b32_e32 v55, v32
	v_mov_b32_e32 v56, v32
	v_mov_b32_e32 v57, v32
	v_mov_b32_e32 v58, v32
	v_mov_b32_e32 v59, v32
	v_mov_b32_e32 v60, v32
	v_mov_b32_e32 v61, v32
	v_mov_b32_e32 v62, v32
	v_mov_b32_e32 v63, v32
	v_mov_b32_e32 v118, 0
	v_mov_b32_e32 v119, 0
	v_mov_b32_e32 v120, 0
	v_mov_b32_e32 v121, 0
	v_mov_b32_e32 v122, 0
	v_mov_b32_e32 v123, 0
	v_mov_b32_e32 v124, 0
	v_mov_b32_e32 v125, 0
.Lap1_step:
	s_add_i32 s54, s54, 1
	s_cmp_lt_i32 s54, s29
	s_cbranch_scc0 .Lap1_w0
	s_waitcnt vmcnt(2)
	s_branch .Lap1_w1

.Lap1_w1:
	s_barrier
	s_cmp_gt_i32 s54, s53
	s_cbranch_scc1 .Lap1_nodma
	v_lshl_add_u64 v[110:111], s[24:25], 0, v[166:167]
	s_add_i32 m0, s38, s61
	s_nop 0
	global_load_lds_dwordx4 v[110:111], off
	v_lshl_add_u64 v[112:113], s[24:25], 0, v[170:171]
	s_add_i32 m0, s57, s61
	s_nop 0
	global_load_lds_dwordx4 v[112:113], off
	s_add_u32 s24, s24, 0x10000
	s_addc_u32 s25, s25, 0
.Lap1_nodma:
	s_cmp_gt_i32 s54, vcc_lo
	s_cbranch_scc1 .Lap1_next
	v_add_u32_e32 v114, s60, v191
	v_add_u32_e32 v115, s60, v190
	v_add_u32_e32 v116, s60, v189
	v_add_u32_e32 v117, s60, v188
	ds_read_b128 v[78:81], v114
	ds_read_b128 v[82:85], v115
	ds_read_b128 v[86:89], v116
	ds_read_b128 v[90:93], v117
	ds_read_b128 v[94:97], v114 offset:8192
	ds_read_b128 v[98:101], v115 offset:8192
	ds_read_b128 v[102:105], v116 offset:8192
	ds_read_b128 v[106:109], v117 offset:8192
	v_exp_f32_e32 v32, v32
	v_exp_f32_e32 v33, v33
	v_exp_f32_e32 v34, v34
	v_exp_f32_e32 v35, v35
	v_pk_add_f32 v[122:123], v[122:123], v[32:33]
	v_pk_add_f32 v[124:125], v[124:125], v[34:35]
	s_waitcnt lgkmcnt(7)
	v_mfma_f32_32x32x16_bf16 v[0:15], v[78:81], v[156:159], 0
	v_exp_f32_e32 v36, v36
	v_exp_f32_e32 v37, v37
	v_exp_f32_e32 v38, v38
	v_exp_f32_e32 v39, v39
	v_pk_add_f32 v[122:123], v[122:123], v[36:37]
	v_pk_add_f32 v[124:125], v[124:125], v[38:39]
	s_waitcnt lgkmcnt(6)
	v_mfma_f32_32x32x16_bf16 v[0:15], v[82:85], v[152:155], v[0:15]
	v_exp_f32_e32 v40, v40
	v_exp_f32_e32 v41, v41
	v_exp_f32_e32 v42, v42
	v_exp_f32_e32 v43, v43
	v_pk_add_f32 v[122:123], v[122:123], v[40:41]
	v_pk_add_f32 v[124:125], v[124:125], v[42:43]
	s_waitcnt lgkmcnt(5)
	v_mfma_f32_32x32x16_bf16 v[0:15], v[86:89], v[148:151], v[0:15]
	v_exp_f32_e32 v44, v44
	v_exp_f32_e32 v45, v45
	v_exp_f32_e32 v46, v46
	v_exp_f32_e32 v47, v47
	v_pk_add_f32 v[122:123], v[122:123], v[44:45]
	v_pk_add_f32 v[124:125], v[124:125], v[46:47]
	s_waitcnt lgkmcnt(4)
	v_mfma_f32_32x32x16_bf16 v[0:15], v[90:93], v[144:147], v[0:15]
	v_add_u32_e32 v114, s60, v187
	v_add_u32_e32 v115, s60, v186
	v_add_u32_e32 v116, s60, v185
	v_add_u32_e32 v117, s60, v184
	ds_read_b128 v[78:81], v114
	ds_read_b128 v[82:85], v115
	ds_read_b128 v[86:89], v116
	ds_read_b128 v[90:93], v117
	v_exp_f32_e32 v48, v48
	v_exp_f32_e32 v49, v49
	v_exp_f32_e32 v50, v50
	v_exp_f32_e32 v51, v51
	v_pk_add_f32 v[122:123], v[122:123], v[48:49]
	v_pk_add_f32 v[124:125], v[124:125], v[50:51]
	s_waitcnt lgkmcnt(7)
	v_mfma_f32_32x32x16_bf16 v[16:31], v[94:97], v[156:159], 0
	v_exp_f32_e32 v52, v52
	v_exp_f32_e32 v53, v53
	v_exp_f32_e32 v54, v54
	v_exp_f32_e32 v55, v55
	v_pk_add_f32 v[122:123], v[122:123], v[52:53]
	v_pk_add_f32 v[124:125], v[124:125], v[54:55]
	s_waitcnt lgkmcnt(6)
	v_mfma_f32_32x32x16_bf16 v[16:31], v[98:101], v[152:155], v[16:31]
	v_exp_f32_e32 v56, v56
	v_exp_f32_e32 v57, v57
	v_exp_f32_e32 v58, v58
	v_exp_f32_e32 v59, v59
	v_pk_add_f32 v[122:123], v[122:123], v[56:57]
	v_pk_add_f32 v[124:125], v[124:125], v[58:59]
	s_waitcnt lgkmcnt(5)
	v_mfma_f32_32x32x16_bf16 v[16:31], v[102:105], v[148:151], v[16:31]
	v_exp_f32_e32 v60, v60
	v_exp_f32_e32 v61, v61
	v_exp_f32_e32 v62, v62
	v_exp_f32_e32 v63, v63
	v_pk_add_f32 v[122:123], v[122:123], v[60:61]
	v_pk_add_f32 v[124:125], v[124:125], v[62:63]
	s_waitcnt lgkmcnt(4)
	v_mfma_f32_32x32x16_bf16 v[16:31], v[106:109], v[144:147], v[16:31]
	ds_read_b128 v[94:97], v114 offset:8192
	ds_read_b128 v[98:101], v115 offset:8192
	ds_read_b128 v[102:105], v116 offset:8192
	ds_read_b128 v[106:109], v117 offset:8192
	v_exp_f32_e32 v0, v0
	v_exp_f32_e32 v1, v1
	v_exp_f32_e32 v2, v2
	v_exp_f32_e32 v3, v3
	v_pk_add_f32 v[118:119], v[118:119], v[0:1]
	v_pk_add_f32 v[120:121], v[120:121], v[2:3]
	s_waitcnt lgkmcnt(7)
	v_mfma_f32_32x32x16_bf16 v[32:47], v[78:81], v[140:143], 0
	v_exp_f32_e32 v4, v4
	v_exp_f32_e32 v5, v5
	v_exp_f32_e32 v6, v6
	v_exp_f32_e32 v7, v7
	v_pk_add_f32 v[118:119], v[118:119], v[4:5]
	v_pk_add_f32 v[120:121], v[120:121], v[6:7]
	s_waitcnt lgkmcnt(6)
	v_mfma_f32_32x32x16_bf16 v[32:47], v[82:85], v[136:139], v[32:47]
	v_exp_f32_e32 v8, v8
	v_exp_f32_e32 v9, v9
	v_exp_f32_e32 v10, v10
	v_exp_f32_e32 v11, v11
	v_pk_add_f32 v[118:119], v[118:119], v[8:9]
	v_pk_add_f32 v[120:121], v[120:121], v[10:11]
	s_waitcnt lgkmcnt(5)
	v_mfma_f32_32x32x16_bf16 v[32:47], v[86:89], v[132:135], v[32:47]
	v_exp_f32_e32 v12, v12
	v_exp_f32_e32 v13, v13
	v_exp_f32_e32 v14, v14
	v_exp_f32_e32 v15, v15
	v_pk_add_f32 v[118:119], v[118:119], v[12:13]
	v_pk_add_f32 v[120:121], v[120:121], v[14:15]
	s_waitcnt lgkmcnt(4)
	v_mfma_f32_32x32x16_bf16 v[32:47], v[90:93], v[128:131], v[32:47]
	v_exp_f32_e32 v16, v16
	v_exp_f32_e32 v17, v17
	v_exp_f32_e32 v18, v18
	v_exp_f32_e32 v19, v19
	v_pk_add_f32 v[118:119], v[118:119], v[16:17]
	v_pk_add_f32 v[120:121], v[120:121], v[18:19]
	s_waitcnt lgkmcnt(3)
	v_mfma_f32_32x32x16_bf16 v[48:63], v[94:97], v[140:143], 0
	v_exp_f32_e32 v20, v20
	v_exp_f32_e32 v21, v21
	v_exp_f32_e32 v22, v22
	v_exp_f32_e32 v23, v23
	v_pk_add_f32 v[118:119], v[118:119], v[20:21]
	v_pk_add_f32 v[120:121], v[120:121], v[22:23]
	s_waitcnt lgkmcnt(2)
	v_mfma_f32_32x32x16_bf16 v[48:63], v[98:101], v[136:139], v[48:63]
	v_exp_f32_e32 v24, v24
	v_exp_f32_e32 v25, v25
	v_exp_f32_e32 v26, v26
	v_exp_f32_e32 v27, v27
	v_pk_add_f32 v[118:119], v[118:119], v[24:25]
	v_pk_add_f32 v[120:121], v[120:121], v[26:27]
	s_waitcnt lgkmcnt(1)
	v_mfma_f32_32x32x16_bf16 v[48:63], v[102:105], v[132:135], v[48:63]
	v_exp_f32_e32 v28, v28
	v_exp_f32_e32 v29, v29
	v_exp_f32_e32 v30, v30
	v_exp_f32_e32 v31, v31
	v_pk_add_f32 v[118:119], v[118:119], v[28:29]
	v_pk_add_f32 v[120:121], v[120:121], v[30:31]
	s_waitcnt lgkmcnt(0)
	v_mfma_f32_32x32x16_bf16 v[48:63], v[106:109], v[128:131], v[48:63]
.Lap1_next:
	s_add_i32 s60, s60, 0x4000
	s_cmp_lg_u32 s60, 0xc000
	s_cselect_b32 s60, s60, 0
	s_add_i32 s61, s61, 0x4000
	s_cmp_lg_u32 s61, 0xc000
	s_cselect_b32 s61, s61, 0
	s_cmp_lt_i32 s54, s29
	s_cbranch_scc1 .Lap1_step
	v_exp_f32_e32 v32, v32
	v_exp_f32_e32 v33, v33
	v_exp_f32_e32 v34, v34
	v_exp_f32_e32 v35, v35
	v_pk_add_f32 v[122:123], v[122:123], v[32:33]
	v_pk_add_f32 v[124:125], v[124:125], v[34:35]
	v_exp_f32_e32 v36, v36
	v_exp_f32_e32 v37, v37
	v_exp_f32_e32 v38, v38
	v_exp_f32_e32 v39, v39
	v_pk_add_f32 v[122:123], v[122:123], v[36:37]
	v_pk_add_f32 v[124:125], v[124:125], v[38:39]
	v_exp_f32_e32 v40, v40
	v_exp_f32_e32 v41, v41
	v_exp_f32_e32 v42, v42
	v_exp_f32_e32 v43, v43
	v_pk_add_f32 v[122:123], v[122:123], v[40:41]
	v_pk_add_f32 v[124:125], v[124:125], v[42:43]
	v_exp_f32_e32 v44, v44
	v_exp_f32_e32 v45, v45
	v_exp_f32_e32 v46, v46
	v_exp_f32_e32 v47, v47
	v_pk_add_f32 v[122:123], v[122:123], v[44:45]
	v_pk_add_f32 v[124:125], v[124:125], v[46:47]
	v_exp_f32_e32 v48, v48
	v_exp_f32_e32 v49, v49
	v_exp_f32_e32 v50, v50
	v_exp_f32_e32 v51, v51
	v_pk_add_f32 v[122:123], v[122:123], v[48:49]
	v_pk_add_f32 v[124:125], v[124:125], v[50:51]
	v_exp_f32_e32 v52, v52
	v_exp_f32_e32 v53, v53
	v_exp_f32_e32 v54, v54
	v_exp_f32_e32 v55, v55
	v_pk_add_f32 v[122:123], v[122:123], v[52:53]
	v_pk_add_f32 v[124:125], v[124:125], v[54:55]
	v_exp_f32_e32 v56, v56
	v_exp_f32_e32 v57, v57
	v_exp_f32_e32 v58, v58
	v_exp_f32_e32 v59, v59
	v_pk_add_f32 v[122:123], v[122:123], v[56:57]
	v_pk_add_f32 v[124:125], v[124:125], v[58:59]
	v_exp_f32_e32 v60, v60
	v_exp_f32_e32 v61, v61
	v_exp_f32_e32 v62, v62
	v_exp_f32_e32 v63, v63
	v_pk_add_f32 v[122:123], v[122:123], v[60:61]
	v_pk_add_f32 v[124:125], v[124:125], v[62:63]
	v_pk_add_f32 v[118:119], v[118:119], v[120:121]
	v_pk_add_f32 v[122:123], v[122:123], v[124:125]
	s_nop 0
	v_add_f32_e32 v73, v118, v119
	v_add_f32_e32 v72, v122, v123
	s_mov_b32 m0, vcc_hi
	s_or_b32 s60, s26, 1
	s_cmp_lt_i32 s60, s39
	s_cselect_b64 s[26:27], -1, 0
	s_cmp_lt_i32 s53, s39
	s_cselect_b64 s[24:25], -1, 0

.LBB0_572:
	v_lshl_add_u32 v168, s22, 8, v140
	v_lshl_or_b32 v238, s24, 8, v147
	v_lshlrev_b32_e32 v238, 1, v238
	v_lshl_add_u32 v164, v168, 11, v238
	v_lshlrev_b32_e32 v168, 2, v168
	global_load_dwordx4 v[170:173], v164, s[10:11]
	global_load_dwordx4 v[174:177], v164, s[10:11] offset:256
	v_add_u32_e32 v238, 0x8000, v164
	global_load_dwordx4 v[178:181], v238, s[10:11]
	global_load_dwordx4 v[182:185], v238, s[10:11] offset:256
	v_add_u32_e32 v238, 0x10000, v164
	global_load_dwordx4 v[186:189], v238, s[10:11]
	global_load_dwordx4 v[190:193], v238, s[10:11] offset:256
	v_add_u32_e32 v238, 0x18000, v164
	global_load_dwordx4 v[194:197], v238, s[10:11]
	global_load_dwordx4 v[198:201], v238, s[10:11] offset:256
	v_add_u32_e32 v238, 0x40000, v164
	global_load_dwordx4 v[202:205], v238, s[10:11]
	global_load_dwordx4 v[206:209], v238, s[10:11] offset:256
	v_add_u32_e32 v238, 0x48000, v164
	global_load_dwordx4 v[210:213], v238, s[10:11]
	global_load_dwordx4 v[214:217], v238, s[10:11] offset:256
	v_add_u32_e32 v238, 0x50000, v164
	global_load_dwordx4 v[218:221], v238, s[10:11]
	global_load_dwordx4 v[222:225], v238, s[10:11] offset:256
	v_add_u32_e32 v238, 0x58000, v164
	global_load_dwordx4 v[226:229], v238, s[10:11]
	global_load_dwordx4 v[244:247], v238, s[10:11] offset:256
	s_waitcnt vmcnt(14)
	v_lshlrev_b32_e32 v132, 16, v170
	v_and_b32_e32 v133, 0xffff0000, v170
	v_lshlrev_b32_e32 v134, 16, v171
	v_and_b32_e32 v135, 0xffff0000, v171
	v_lshlrev_b32_e32 v166, 16, v172
	v_and_b32_e32 v167, 0xffff0000, v172
	v_lshlrev_b32_e32 v230, 16, v173
	v_and_b32_e32 v231, 0xffff0000, v173
	v_lshlrev_b32_e32 v232, 16, v174
	v_and_b32_e32 v233, 0xffff0000, v174
	v_lshlrev_b32_e32 v234, 16, v175
	v_and_b32_e32 v235, 0xffff0000, v175
	v_lshlrev_b32_e32 v236, 16, v176
	v_and_b32_e32 v237, 0xffff0000, v176
	v_lshlrev_b32_e32 v240, 16, v177
	v_and_b32_e32 v241, 0xffff0000, v177
	v_pk_add_f32 v[124:125], v[124:125], v[132:133]
	v_pk_add_f32 v[126:127], v[126:127], v[134:135]
	v_pk_add_f32 v[120:121], v[120:121], v[166:167]
	v_pk_add_f32 v[122:123], v[122:123], v[230:231]
	v_pk_add_f32 v[116:117], v[116:117], v[232:233]
	v_pk_add_f32 v[118:119], v[118:119], v[234:235]
	v_pk_add_f32 v[112:113], v[112:113], v[236:237]
	v_pk_add_f32 v[114:115], v[114:115], v[240:241]
	v_pk_mul_f32 v[132:133], v[124:125], v[124:125]
	v_pk_mul_f32 v[134:135], v[126:127], v[126:127]
	v_pk_fma_f32 v[132:133], v[120:121], v[120:121], v[132:133]
	v_pk_fma_f32 v[134:135], v[122:123], v[122:123], v[134:135]
	v_pk_fma_f32 v[132:133], v[116:117], v[116:117], v[132:133]
	v_pk_fma_f32 v[134:135], v[118:119], v[118:119], v[134:135]
	v_pk_fma_f32 v[132:133], v[112:113], v[112:113], v[132:133]
	v_pk_fma_f32 v[134:135], v[114:115], v[114:115], v[134:135]
	v_cvt_pk_bf16_f32 v124, v124, v125
	v_cvt_pk_bf16_f32 v125, v126, v127
	v_cvt_pk_bf16_f32 v126, v120, v121
	v_cvt_pk_bf16_f32 v127, v122, v123
	v_cvt_pk_bf16_f32 v116, v116, v117
	v_cvt_pk_bf16_f32 v117, v118, v119
	v_cvt_pk_bf16_f32 v118, v112, v113
	v_cvt_pk_bf16_f32 v119, v114, v115
	v_pk_add_f32 v[132:133], v[132:133], v[134:135]
	global_store_dwordx4 v164, v[124:127], s[46:47]
	global_store_dwordx4 v164, v[116:119], s[46:47] offset:256
	v_add_f32_e32 v120, v132, v133
	s_waitcnt vmcnt(14)
	v_lshlrev_b32_e32 v132, 16, v178
	v_and_b32_e32 v133, 0xffff0000, v178
	v_lshlrev_b32_e32 v134, 16, v179
	v_and_b32_e32 v135, 0xffff0000, v179
	v_lshlrev_b32_e32 v166, 16, v180
	v_and_b32_e32 v167, 0xffff0000, v180
	v_lshlrev_b32_e32 v230, 16, v181
	v_and_b32_e32 v231, 0xffff0000, v181
	v_lshlrev_b32_e32 v232, 16, v182
	v_and_b32_e32 v233, 0xffff0000, v182
	v_lshlrev_b32_e32 v234, 16, v183
	v_and_b32_e32 v235, 0xffff0000, v183
	v_lshlrev_b32_e32 v236, 16, v184
	v_and_b32_e32 v237, 0xffff0000, v184
	v_lshlrev_b32_e32 v240, 16, v185
	v_and_b32_e32 v241, 0xffff0000, v185
	v_pk_add_f32 v[108:109], v[108:109], v[132:133]
	v_pk_add_f32 v[110:111], v[110:111], v[134:135]
	v_pk_add_f32 v[104:105], v[104:105], v[166:167]
	v_pk_add_f32 v[106:107], v[106:107], v[230:231]
	v_pk_add_f32 v[100:101], v[100:101], v[232:233]
	v_pk_add_f32 v[102:103], v[102:103], v[234:235]
	v_pk_add_f32 v[96:97], v[96:97], v[236:237]
	v_pk_add_f32 v[98:99], v[98:99], v[240:241]
	v_pk_mul_f32 v[132:133], v[108:109], v[108:109]
	v_pk_mul_f32 v[134:135], v[110:111], v[110:111]
	v_pk_fma_f32 v[132:133], v[104:105], v[104:105], v[132:133]
	v_pk_fma_f32 v[134:135], v[106:107], v[106:107], v[134:135]
	v_pk_fma_f32 v[132:133], v[100:101], v[100:101], v[132:133]
	v_pk_fma_f32 v[134:135], v[102:103], v[102:103], v[134:135]
	v_pk_fma_f32 v[132:133], v[96:97], v[96:97], v[132:133]
	v_pk_fma_f32 v[134:135], v[98:99], v[98:99], v[134:135]
	v_cvt_pk_bf16_f32 v108, v108, v109
	v_cvt_pk_bf16_f32 v109, v110, v111
	v_cvt_pk_bf16_f32 v110, v104, v105
	v_cvt_pk_bf16_f32 v111, v106, v107
	v_cvt_pk_bf16_f32 v100, v100, v101
	v_cvt_pk_bf16_f32 v101, v102, v103
	v_cvt_pk_bf16_f32 v102, v96, v97
	v_cvt_pk_bf16_f32 v103, v98, v99
	v_add_u32_e32 v238, 0x8000, v164
	v_pk_add_f32 v[132:133], v[132:133], v[134:135]
	global_store_dwordx4 v238, v[108:111], s[46:47]
	global_store_dwordx4 v238, v[100:103], s[46:47] offset:256
	v_add_f32_e32 v104, v132, v133
	s_waitcnt vmcnt(14)
	v_lshlrev_b32_e32 v132, 16, v186
	v_and_b32_e32 v133, 0xffff0000, v186
	v_lshlrev_b32_e32 v134, 16, v187
	v_and_b32_e32 v135, 0xffff0000, v187
	v_lshlrev_b32_e32 v166, 16, v188
	v_and_b32_e32 v167, 0xffff0000, v188
	v_lshlrev_b32_e32 v230, 16, v189
	v_and_b32_e32 v231, 0xffff0000, v189
	v_lshlrev_b32_e32 v232, 16, v190
	v_and_b32_e32 v233, 0xffff0000, v190
	v_lshlrev_b32_e32 v234, 16, v191
	v_and_b32_e32 v235, 0xffff0000, v191
	v_lshlrev_b32_e32 v236, 16, v192
	v_and_b32_e32 v237, 0xffff0000, v192
	v_lshlrev_b32_e32 v240, 16, v193
	v_and_b32_e32 v241, 0xffff0000, v193
	v_pk_add_f32 v[92:93], v[92:93], v[132:133]
	v_pk_add_f32 v[94:95], v[94:95], v[134:135]
	v_pk_add_f32 v[88:89], v[88:89], v[166:167]
	v_pk_add_f32 v[90:91], v[90:91], v[230:231]
	v_pk_add_f32 v[84:85], v[84:85], v[232:233]
	v_pk_add_f32 v[86:87], v[86:87], v[234:235]
	v_pk_add_f32 v[80:81], v[80:81], v[236:237]
	v_pk_add_f32 v[82:83], v[82:83], v[240:241]
	v_pk_mul_f32 v[132:133], v[92:93], v[92:93]
	v_pk_mul_f32 v[134:135], v[94:95], v[94:95]
	v_pk_fma_f32 v[132:133], v[88:89], v[88:89], v[132:133]
	v_pk_fma_f32 v[134:135], v[90:91], v[90:91], v[134:135]
	v_pk_fma_f32 v[132:133], v[84:85], v[84:85], v[132:133]
	v_pk_fma_f32 v[134:135], v[86:87], v[86:87], v[134:135]
	v_pk_fma_f32 v[132:133], v[80:81], v[80:81], v[132:133]
	v_pk_fma_f32 v[134:135], v[82:83], v[82:83], v[134:135]
	v_cvt_pk_bf16_f32 v92, v92, v93
	v_cvt_pk_bf16_f32 v93, v94, v95
	v_cvt_pk_bf16_f32 v94, v88, v89
	v_cvt_pk_bf16_f32 v95, v90, v91
	v_cvt_pk_bf16_f32 v84, v84, v85
	v_cvt_pk_bf16_f32 v85, v86, v87
	v_cvt_pk_bf16_f32 v86, v80, v81
	v_cvt_pk_bf16_f32 v87, v82, v83
	v_add_u32_e32 v238, 0x10000, v164
	v_pk_add_f32 v[132:133], v[132:133], v[134:135]
	global_store_dwordx4 v238, v[92:95], s[46:47]
	global_store_dwordx4 v238, v[84:87], s[46:47] offset:256
	v_add_f32_e32 v88, v132, v133
	s_waitcnt vmcnt(14)
	v_lshlrev_b32_e32 v132, 16, v194
	v_and_b32_e32 v133, 0xffff0000, v194
	v_lshlrev_b32_e32 v134, 16, v195
	v_and_b32_e32 v135, 0xffff0000, v195
	v_lshlrev_b32_e32 v166, 16, v196
	v_and_b32_e32 v167, 0xffff0000, v196
	v_lshlrev_b32_e32 v230, 16, v197
	v_and_b32_e32 v231, 0xffff0000, v197
	v_lshlrev_b32_e32 v232, 16, v198
	v_and_b32_e32 v233, 0xffff0000, v198
	v_lshlrev_b32_e32 v234, 16, v199
	v_and_b32_e32 v235, 0xffff0000, v199
	v_lshlrev_b32_e32 v236, 16, v200
	v_and_b32_e32 v237, 0xffff0000, v200
	v_lshlrev_b32_e32 v240, 16, v201
	v_and_b32_e32 v241, 0xffff0000, v201
	v_pk_add_f32 v[76:77], v[76:77], v[132:133]
	v_pk_add_f32 v[78:79], v[78:79], v[134:135]
	v_pk_add_f32 v[72:73], v[72:73], v[166:167]
	v_pk_add_f32 v[74:75], v[74:75], v[230:231]
	v_pk_add_f32 v[68:69], v[68:69], v[232:233]
	v_pk_add_f32 v[70:71], v[70:71], v[234:235]
	v_pk_add_f32 v[64:65], v[64:65], v[236:237]
	v_pk_add_f32 v[66:67], v[66:67], v[240:241]
	v_pk_mul_f32 v[132:133], v[76:77], v[76:77]
	v_pk_mul_f32 v[134:135], v[78:79], v[78:79]
	v_pk_fma_f32 v[132:133], v[72:73], v[72:73], v[132:133]
	v_pk_fma_f32 v[134:135], v[74:75], v[74:75], v[134:135]
	v_pk_fma_f32 v[132:133], v[68:69], v[68:69], v[132:133]
	v_pk_fma_f32 v[134:135], v[70:71], v[70:71], v[134:135]
	v_pk_fma_f32 v[132:133], v[64:65], v[64:65], v[132:133]
	v_pk_fma_f32 v[134:135], v[66:67], v[66:67], v[134:135]
	v_cvt_pk_bf16_f32 v76, v76, v77
	v_cvt_pk_bf16_f32 v77, v78, v79
	v_cvt_pk_bf16_f32 v78, v72, v73
	v_cvt_pk_bf16_f32 v79, v74, v75
	v_cvt_pk_bf16_f32 v68, v68, v69
	v_cvt_pk_bf16_f32 v69, v70, v71
	v_cvt_pk_bf16_f32 v70, v64, v65
	v_cvt_pk_bf16_f32 v71, v66, v67
	v_add_u32_e32 v238, 0x18000, v164
	v_pk_add_f32 v[132:133], v[132:133], v[134:135]
	global_store_dwordx4 v238, v[76:79], s[46:47]
	global_store_dwordx4 v238, v[68:71], s[46:47] offset:256
	v_add_f32_e32 v72, v132, v133
	s_waitcnt vmcnt(14)
	v_lshlrev_b32_e32 v132, 16, v202
	v_and_b32_e32 v133, 0xffff0000, v202
	v_lshlrev_b32_e32 v134, 16, v203
	v_and_b32_e32 v135, 0xffff0000, v203
	v_lshlrev_b32_e32 v166, 16, v204
	v_and_b32_e32 v167, 0xffff0000, v204
	v_lshlrev_b32_e32 v230, 16, v205
	v_and_b32_e32 v231, 0xffff0000, v205
	v_lshlrev_b32_e32 v232, 16, v206
	v_and_b32_e32 v233, 0xffff0000, v206
	v_lshlrev_b32_e32 v234, 16, v207
	v_and_b32_e32 v235, 0xffff0000, v207
	v_lshlrev_b32_e32 v236, 16, v208
	v_and_b32_e32 v237, 0xffff0000, v208
	v_lshlrev_b32_e32 v240, 16, v209
	v_and_b32_e32 v241, 0xffff0000, v209
	v_pk_add_f32 v[60:61], v[60:61], v[132:133]
	v_pk_add_f32 v[62:63], v[62:63], v[134:135]
	v_pk_add_f32 v[56:57], v[56:57], v[166:167]
	v_pk_add_f32 v[58:59], v[58:59], v[230:231]
	v_pk_add_f32 v[52:53], v[52:53], v[232:233]
	v_pk_add_f32 v[54:55], v[54:55], v[234:235]
	v_pk_add_f32 v[48:49], v[48:49], v[236:237]
	v_pk_add_f32 v[50:51], v[50:51], v[240:241]
	v_pk_mul_f32 v[132:133], v[60:61], v[60:61]
	v_pk_mul_f32 v[134:135], v[62:63], v[62:63]
	v_pk_fma_f32 v[132:133], v[56:57], v[56:57], v[132:133]
	v_pk_fma_f32 v[134:135], v[58:59], v[58:59], v[134:135]
	v_pk_fma_f32 v[132:133], v[52:53], v[52:53], v[132:133]
	v_pk_fma_f32 v[134:135], v[54:55], v[54:55], v[134:135]
	v_pk_fma_f32 v[132:133], v[48:49], v[48:49], v[132:133]
	v_pk_fma_f32 v[134:135], v[50:51], v[50:51], v[134:135]
	v_cvt_pk_bf16_f32 v60, v60, v61
	v_cvt_pk_bf16_f32 v61, v62, v63
	v_cvt_pk_bf16_f32 v62, v56, v57
	v_cvt_pk_bf16_f32 v63, v58, v59
	v_cvt_pk_bf16_f32 v52, v52, v53
	v_cvt_pk_bf16_f32 v53, v54, v55
	v_cvt_pk_bf16_f32 v54, v48, v49
	v_cvt_pk_bf16_f32 v55, v50, v51
	v_add_u32_e32 v238, 0x40000, v164
	v_pk_add_f32 v[132:133], v[132:133], v[134:135]
	global_store_dwordx4 v238, v[60:63], s[46:47]
	global_store_dwordx4 v238, v[52:55], s[46:47] offset:256
	v_add_f32_e32 v56, v132, v133
	s_waitcnt vmcnt(14)
	v_lshlrev_b32_e32 v132, 16, v210
	v_and_b32_e32 v133, 0xffff0000, v210
	v_lshlrev_b32_e32 v134, 16, v211
	v_and_b32_e32 v135, 0xffff0000, v211
	v_lshlrev_b32_e32 v166, 16, v212
	v_and_b32_e32 v167, 0xffff0000, v212
	v_lshlrev_b32_e32 v230, 16, v213
	v_and_b32_e32 v231, 0xffff0000, v213
	v_lshlrev_b32_e32 v232, 16, v214
	v_and_b32_e32 v233, 0xffff0000, v214
	v_lshlrev_b32_e32 v234, 16, v215
	v_and_b32_e32 v235, 0xffff0000, v215
	v_lshlrev_b32_e32 v236, 16, v216
	v_and_b32_e32 v237, 0xffff0000, v216
	v_lshlrev_b32_e32 v240, 16, v217
	v_and_b32_e32 v241, 0xffff0000, v217
	v_pk_add_f32 v[44:45], v[44:45], v[132:133]
	v_pk_add_f32 v[46:47], v[46:47], v[134:135]
	v_pk_add_f32 v[40:41], v[40:41], v[166:167]
	v_pk_add_f32 v[42:43], v[42:43], v[230:231]
	v_pk_add_f32 v[36:37], v[36:37], v[232:233]
	v_pk_add_f32 v[38:39], v[38:39], v[234:235]
	v_pk_add_f32 v[32:33], v[32:33], v[236:237]
	v_pk_add_f32 v[34:35], v[34:35], v[240:241]
	v_pk_mul_f32 v[132:133], v[44:45], v[44:45]
	v_pk_mul_f32 v[134:135], v[46:47], v[46:47]
	v_pk_fma_f32 v[132:133], v[40:41], v[40:41], v[132:133]
	v_pk_fma_f32 v[134:135], v[42:43], v[42:43], v[134:135]
	v_pk_fma_f32 v[132:133], v[36:37], v[36:37], v[132:133]
	v_pk_fma_f32 v[134:135], v[38:39], v[38:39], v[134:135]
	v_pk_fma_f32 v[132:133], v[32:33], v[32:33], v[132:133]
	v_pk_fma_f32 v[134:135], v[34:35], v[34:35], v[134:135]
	v_cvt_pk_bf16_f32 v44, v44, v45
	v_cvt_pk_bf16_f32 v45, v46, v47
	v_cvt_pk_bf16_f32 v46, v40, v41
	v_cvt_pk_bf16_f32 v47, v42, v43
	v_cvt_pk_bf16_f32 v36, v36, v37
	v_cvt_pk_bf16_f32 v37, v38, v39
	v_cvt_pk_bf16_f32 v38, v32, v33
	v_cvt_pk_bf16_f32 v39, v34, v35
	v_add_u32_e32 v238, 0x48000, v164
	v_pk_add_f32 v[132:133], v[132:133], v[134:135]
	global_store_dwordx4 v238, v[44:47], s[46:47]
	global_store_dwordx4 v238, v[36:39], s[46:47] offset:256
	v_add_f32_e32 v40, v132, v133
	s_waitcnt vmcnt(14)
	v_lshlrev_b32_e32 v132, 16, v218
	v_and_b32_e32 v133, 0xffff0000, v218
	v_lshlrev_b32_e32 v134, 16, v219
	v_and_b32_e32 v135, 0xffff0000, v219
	v_lshlrev_b32_e32 v166, 16, v220
	v_and_b32_e32 v167, 0xffff0000, v220
	v_lshlrev_b32_e32 v230, 16, v221
	v_and_b32_e32 v231, 0xffff0000, v221
	v_lshlrev_b32_e32 v232, 16, v222
	v_and_b32_e32 v233, 0xffff0000, v222
	v_lshlrev_b32_e32 v234, 16, v223
	v_and_b32_e32 v235, 0xffff0000, v223
	v_lshlrev_b32_e32 v236, 16, v224
	v_and_b32_e32 v237, 0xffff0000, v224
	v_lshlrev_b32_e32 v240, 16, v225
	v_and_b32_e32 v241, 0xffff0000, v225
	v_pk_add_f32 v[28:29], v[28:29], v[132:133]
	v_pk_add_f32 v[30:31], v[30:31], v[134:135]
	v_pk_add_f32 v[24:25], v[24:25], v[166:167]
	v_pk_add_f32 v[26:27], v[26:27], v[230:231]
	v_pk_add_f32 v[20:21], v[20:21], v[232:233]
	v_pk_add_f32 v[22:23], v[22:23], v[234:235]
	v_pk_add_f32 v[16:17], v[16:17], v[236:237]
	v_pk_add_f32 v[18:19], v[18:19], v[240:241]
	v_pk_mul_f32 v[132:133], v[28:29], v[28:29]
	v_pk_mul_f32 v[134:135], v[30:31], v[30:31]
	v_pk_fma_f32 v[132:133], v[24:25], v[24:25], v[132:133]
	v_pk_fma_f32 v[134:135], v[26:27], v[26:27], v[134:135]
	v_pk_fma_f32 v[132:133], v[20:21], v[20:21], v[132:133]
	v_pk_fma_f32 v[134:135], v[22:23], v[22:23], v[134:135]
	v_pk_fma_f32 v[132:133], v[16:17], v[16:17], v[132:133]
	v_pk_fma_f32 v[134:135], v[18:19], v[18:19], v[134:135]
	v_cvt_pk_bf16_f32 v28, v28, v29
	v_cvt_pk_bf16_f32 v29, v30, v31
	v_cvt_pk_bf16_f32 v30, v24, v25
	v_cvt_pk_bf16_f32 v31, v26, v27
	v_cvt_pk_bf16_f32 v20, v20, v21
	v_cvt_pk_bf16_f32 v21, v22, v23
	v_cvt_pk_bf16_f32 v22, v16, v17
	v_cvt_pk_bf16_f32 v23, v18, v19
	v_add_u32_e32 v238, 0x50000, v164
	v_pk_add_f32 v[132:133], v[132:133], v[134:135]
	global_store_dwordx4 v238, v[28:31], s[46:47]
	global_store_dwordx4 v238, v[20:23], s[46:47] offset:256
	v_add_f32_e32 v24, v132, v133
	s_waitcnt vmcnt(14)
	v_lshlrev_b32_e32 v132, 16, v226
	v_and_b32_e32 v133, 0xffff0000, v226
	v_lshlrev_b32_e32 v134, 16, v227
	v_and_b32_e32 v135, 0xffff0000, v227
	v_lshlrev_b32_e32 v166, 16, v228
	v_and_b32_e32 v167, 0xffff0000, v228
	v_lshlrev_b32_e32 v230, 16, v229
	v_and_b32_e32 v231, 0xffff0000, v229
	v_lshlrev_b32_e32 v232, 16, v244
	v_and_b32_e32 v233, 0xffff0000, v244
	v_lshlrev_b32_e32 v234, 16, v245
	v_and_b32_e32 v235, 0xffff0000, v245
	v_lshlrev_b32_e32 v236, 16, v246
	v_and_b32_e32 v237, 0xffff0000, v246
	v_lshlrev_b32_e32 v240, 16, v247
	v_and_b32_e32 v241, 0xffff0000, v247
	v_pk_add_f32 v[12:13], v[12:13], v[132:133]
	v_pk_add_f32 v[14:15], v[14:15], v[134:135]
	v_pk_add_f32 v[8:9], v[8:9], v[166:167]
	v_pk_add_f32 v[10:11], v[10:11], v[230:231]
	v_pk_add_f32 v[4:5], v[4:5], v[232:233]
	v_pk_add_f32 v[6:7], v[6:7], v[234:235]
	v_pk_add_f32 v[0:1], v[0:1], v[236:237]
	v_pk_add_f32 v[2:3], v[2:3], v[240:241]
	v_pk_mul_f32 v[132:133], v[12:13], v[12:13]
	v_pk_mul_f32 v[134:135], v[14:15], v[14:15]
	v_pk_fma_f32 v[132:133], v[8:9], v[8:9], v[132:133]
	v_pk_fma_f32 v[134:135], v[10:11], v[10:11], v[134:135]
	v_pk_fma_f32 v[132:133], v[4:5], v[4:5], v[132:133]
	v_pk_fma_f32 v[134:135], v[6:7], v[6:7], v[134:135]
	v_pk_fma_f32 v[132:133], v[0:1], v[0:1], v[132:133]
	v_pk_fma_f32 v[134:135], v[2:3], v[2:3], v[134:135]
	v_cvt_pk_bf16_f32 v12, v12, v13
	v_cvt_pk_bf16_f32 v13, v14, v15
	v_cvt_pk_bf16_f32 v14, v8, v9
	v_cvt_pk_bf16_f32 v15, v10, v11
	v_cvt_pk_bf16_f32 v4, v4, v5
	v_cvt_pk_bf16_f32 v5, v6, v7
	v_cvt_pk_bf16_f32 v6, v0, v1
	v_cvt_pk_bf16_f32 v7, v2, v3
	v_add_u32_e32 v238, 0x58000, v164
	v_pk_add_f32 v[132:133], v[132:133], v[134:135]
	global_store_dwordx4 v238, v[12:15], s[46:47]
	global_store_dwordx4 v238, v[4:7], s[46:47] offset:256
	v_add_f32_e32 v8, v132, v133
	ds_bpermute_b32 v121, v163, v120
	ds_bpermute_b32 v105, v163, v104
	ds_bpermute_b32 v89, v163, v88
	ds_bpermute_b32 v73, v163, v72
	ds_bpermute_b32 v57, v163, v56
	ds_bpermute_b32 v41, v163, v40
	ds_bpermute_b32 v25, v163, v24
	ds_bpermute_b32 v9, v163, v8
	s_waitcnt lgkmcnt(7)
	v_add_f32_e32 v120, v120, v121
	s_waitcnt lgkmcnt(6)
	v_add_f32_e32 v104, v104, v105
	s_waitcnt lgkmcnt(5)
	v_add_f32_e32 v88, v88, v89
	s_waitcnt lgkmcnt(4)
	v_add_f32_e32 v72, v72, v73
	s_waitcnt lgkmcnt(3)
	v_add_f32_e32 v56, v56, v57
	s_waitcnt lgkmcnt(2)
	v_add_f32_e32 v40, v40, v41
	s_waitcnt lgkmcnt(1)
	v_add_f32_e32 v24, v24, v25
	s_waitcnt lgkmcnt(0)
	v_add_f32_e32 v8, v8, v9
	ds_bpermute_b32 v121, v169, v120
	ds_bpermute_b32 v105, v169, v104
	ds_bpermute_b32 v89, v169, v88
	ds_bpermute_b32 v73, v169, v72
	ds_bpermute_b32 v57, v169, v56
	ds_bpermute_b32 v41, v169, v40
	ds_bpermute_b32 v25, v169, v24
	ds_bpermute_b32 v9, v169, v8
	s_waitcnt lgkmcnt(7)
	v_add_f32_e32 v120, v120, v121
	s_waitcnt lgkmcnt(6)
	v_add_f32_e32 v104, v104, v105
	s_waitcnt lgkmcnt(5)
	v_add_f32_e32 v88, v88, v89
	s_waitcnt lgkmcnt(4)
	v_add_f32_e32 v72, v72, v73
	s_waitcnt lgkmcnt(3)
	v_add_f32_e32 v56, v56, v57
	s_waitcnt lgkmcnt(2)
	v_add_f32_e32 v40, v40, v41
	s_waitcnt lgkmcnt(1)
	v_add_f32_e32 v24, v24, v25
	s_waitcnt lgkmcnt(0)
	v_add_f32_e32 v8, v8, v9
	s_and_saveexec_b64 s[22:23], s[4:5]
	global_atomic_add_f32 v168, v120, s[42:43]
	global_atomic_add_f32 v168, v104, s[42:43] offset:64
	global_atomic_add_f32 v168, v88, s[42:43] offset:128
	global_atomic_add_f32 v168, v72, s[42:43] offset:192
	global_atomic_add_f32 v168, v56, s[42:43] offset:512
	global_atomic_add_f32 v168, v40, s[42:43] offset:576
	global_atomic_add_f32 v168, v24, s[42:43] offset:640
	global_atomic_add_f32 v168, v8, s[42:43] offset:704
	s_or_b64 exec, exec, s[22:23]
	s_andn2_b64 vcc, exec, s[6:7]
	s_mov_b64 s[6:7], -1
	s_cbranch_vccnz .LBB0_561
	s_andn2_b64 vcc, exec, s[0:1]
	s_cbranch_vccnz .LBB0_560
	s_barrier
	s_branch .LBB0_560

	.amdhsa_kernel _Z4mega6Params
		.amdhsa_group_segment_fixed_size 0
		.amdhsa_private_segment_fixed_size 0
		.amdhsa_kernarg_size 488
		.amdhsa_user_sgpr_count 2
		.amdhsa_user_sgpr_dispatch_ptr 0
		.amdhsa_user_sgpr_queue_ptr 0
		.amdhsa_user_sgpr_kernarg_segment_ptr 1
		.amdhsa_user_sgpr_dispatch_id 0
		.amdhsa_user_sgpr_kernarg_preload_length 0
		.amdhsa_user_sgpr_kernarg_preload_offset 0
		.amdhsa_user_sgpr_private_segment_size 0
		.amdhsa_uses_dynamic_stack 0
		.amdhsa_enable_private_segment 0
		.amdhsa_system_sgpr_workgroup_id_x 1
		.amdhsa_system_sgpr_workgroup_id_y 0
		.amdhsa_system_sgpr_workgroup_id_z 0
		.amdhsa_system_sgpr_workgroup_info 0
		.amdhsa_system_vgpr_workitem_id 2
		.amdhsa_next_free_vgpr 248
		.amdhsa_next_free_sgpr 98
		.amdhsa_accum_offset 248
		.amdhsa_reserve_vcc 1
		.amdhsa_float_round_mode_32 0
		.amdhsa_float_round_mode_16_64 0
		.amdhsa_float_denorm_mode_32 3
		.amdhsa_float_denorm_mode_16_64 3
		.amdhsa_dx10_clamp 1
		.amdhsa_ieee_mode 1
		.amdhsa_fp16_overflow 0
		.amdhsa_tg_split 0
		.amdhsa_exception_fp_ieee_invalid_op 0
		.amdhsa_exception_fp_denorm_src 0
		.amdhsa_exception_fp_ieee_div_zero 0
		.amdhsa_exception_fp_ieee_overflow 0
		.amdhsa_exception_fp_ieee_underflow 0
		.amdhsa_exception_fp_ieee_inexact 0
		.amdhsa_exception_int_div_zero 0
	.end_amdhsa_kernel

amdhsa.kernels:
  - .agpr_count:     0
    .args:
      - .offset:         0
        .size:           232
        .value_kind:     by_value
      - .offset:         232
        .size:           4
        .value_kind:     hidden_block_count_x
      - .offset:         236
        .size:           4
        .value_kind:     hidden_block_count_y
      - .offset:         240
        .size:           4
        .value_kind:     hidden_block_count_z
      - .offset:         244
        .size:           2
        .value_kind:     hidden_group_size_x
      - .offset:         246
        .size:           2
        .value_kind:     hidden_group_size_y
      - .offset:         248
        .size:           2
        .value_kind:     hidden_group_size_z
      - .offset:         250
        .size:           2
        .value_kind:     hidden_remainder_x
      - .offset:         252
        .size:           2
        .value_kind:     hidden_remainder_y
      - .offset:         254
        .size:           2
        .value_kind:     hidden_remainder_z
      - .offset:         272
        .size:           8
        .value_kind:     hidden_global_offset_x
      - .offset:         280
        .size:           8
        .value_kind:     hidden_global_offset_y
      - .offset:         288
        .size:           8
        .value_kind:     hidden_global_offset_z
      - .offset:         296
        .size:           2
        .value_kind:     hidden_grid_dims
      - .offset:         320
        .size:           8
        .value_kind:     hidden_multigrid_sync_arg
      - .offset:         352
        .size:           4
        .value_kind:     hidden_dynamic_lds_size
    .group_segment_fixed_size: 0
    .kernarg_segment_align: 8
    .kernarg_segment_size: 488
    .language:       OpenCL C
    .language_version:
      - 2
      - 0
    .max_flat_workgroup_size: 512
    .name:           _Z4mega6Params
    .private_segment_fixed_size: 0
    .sgpr_count:     104
    .sgpr_spill_count: 69
    .symbol:         _Z4mega6Params.kd
    .uniform_work_group_size: 1
    .uses_dynamic_stack: false
    .vgpr_count:     248
    .vgpr_spill_count: 0
    .wavefront_size: 64
